# v57 + leading half starts the up epilogue before its alignment barrier (barrier moved behind the second output store)
# baseline (speedup 1.0000x reference)
.LBB0_159:
	s_add_u32 s0, s22, 0xfff80080
	s_addc_u32 s1, s23, -1
	s_add_i32 s51, 0, 0x10000
	s_cmp_eq_u32 s50, 28
	s_cselect_b32 s27, s15, s1
	s_cselect_b32 s26, s46, s0
	v_add_u32_e32 v140, s51, v143
	s_cselect_b32 s25, s13, s49
	s_cselect_b32 s24, s47, s48
	s_add_i32 s0, 0, 0x14000
	ds_read_b128 v[146:149], v140
	ds_read_b128 v[150:153], v140 offset:1024
	ds_read_b128 v[154:157], v140 offset:2048
	ds_read_b128 v[158:161], v140 offset:3072
	v_add_u32_e32 v140, s0, v143
	ds_read_b128 v[162:165], v140
	ds_read_b128 v[166:169], v140 offset:1024
	ds_read_b128 v[170:173], v140 offset:2048
	ds_read_b128 v[174:177], v140 offset:3072
	s_add_i32 m0, s35, 0xc000
	ds_read_b128 v[178:181], v144
	ds_read_b128 v[182:185], v144 offset:1024
	ds_read_b128 v[192:195], v144 offset:2048
	ds_read_b128 v[196:199], v144 offset:3072
	ds_read_b128 v[200:203], v144 offset:4096
	ds_read_b128 v[204:207], v144 offset:5120
	ds_read_b128 v[208:211], v144 offset:6144
	ds_read_b128 v[212:215], v144 offset:7168
	global_load_lds_dwordx4 v136, s[22:23]
	s_add_i32 m0, s35, 0xe000
	s_nop 0
	global_load_lds_dwordx4 v138, s[22:23]
	s_waitcnt vmcnt(8)
	s_waitcnt lgkmcnt(0)
	s_setprio 1
	s_barrier

	v_mfma_f32_16x16x32_bf16 v[126:129], v[146:149], v[178:181], v[126:129]
	v_mfma_f32_16x16x32_bf16 v[126:129], v[150:153], v[182:185], v[126:129]
	v_mfma_f32_16x16x32_bf16 v[118:121], v[158:161], v[182:185], v[118:121]
	v_mfma_f32_16x16x32_bf16 v[118:121], v[154:157], v[178:181], v[118:121]
	v_mfma_f32_16x16x32_bf16 v[102:105], v[154:157], v[192:195], v[102:105]
	v_mfma_f32_16x16x32_bf16 v[102:105], v[158:161], v[196:199], v[102:105]
	v_mfma_f32_16x16x32_bf16 v[110:113], v[150:153], v[196:199], v[110:113]
	v_mfma_f32_16x16x32_bf16 v[110:113], v[146:149], v[192:195], v[110:113]
	v_mfma_f32_16x16x32_bf16 v[94:97], v[146:149], v[200:203], v[94:97]
	v_mfma_f32_16x16x32_bf16 v[94:97], v[150:153], v[204:207], v[94:97]
	v_mfma_f32_16x16x32_bf16 v[86:89], v[158:161], v[204:207], v[86:89]
	v_mfma_f32_16x16x32_bf16 v[86:89], v[154:157], v[200:203], v[86:89]
	v_mfma_f32_16x16x32_bf16 v[70:73], v[154:157], v[208:211], v[70:73]
	v_mfma_f32_16x16x32_bf16 v[70:73], v[158:161], v[212:215], v[70:73]
	v_mfma_f32_16x16x32_bf16 v[78:81], v[150:153], v[212:215], v[78:81]
	v_mfma_f32_16x16x32_bf16 v[78:81], v[146:149], v[208:211], v[78:81]


	v_mfma_f32_16x16x32_bf16 v[122:125], v[162:165], v[178:181], v[122:125]
	v_mfma_f32_16x16x32_bf16 v[122:125], v[166:169], v[182:185], v[122:125]
	v_mfma_f32_16x16x32_bf16 v[114:117], v[174:177], v[182:185], v[114:117]
	v_mfma_f32_16x16x32_bf16 v[114:117], v[170:173], v[178:181], v[114:117]
	v_mfma_f32_16x16x32_bf16 v[98:101], v[170:173], v[192:195], v[98:101]
	v_mfma_f32_16x16x32_bf16 v[98:101], v[174:177], v[196:199], v[98:101]
	v_mfma_f32_16x16x32_bf16 v[106:109], v[166:169], v[196:199], v[106:109]
	v_mfma_f32_16x16x32_bf16 v[106:109], v[162:165], v[192:195], v[106:109]
	v_mfma_f32_16x16x32_bf16 v[90:93], v[162:165], v[200:203], v[90:93]
	v_mfma_f32_16x16x32_bf16 v[90:93], v[166:169], v[204:207], v[90:93]
	v_mfma_f32_16x16x32_bf16 v[82:85], v[174:177], v[204:207], v[82:85]
	v_mfma_f32_16x16x32_bf16 v[82:85], v[170:173], v[200:203], v[82:85]
	v_mfma_f32_16x16x32_bf16 v[66:69], v[170:173], v[208:211], v[66:69]
	v_mfma_f32_16x16x32_bf16 v[66:69], v[174:177], v[212:215], v[66:69]
	v_mfma_f32_16x16x32_bf16 v[74:77], v[166:169], v[212:215], v[74:77]
	v_mfma_f32_16x16x32_bf16 v[74:77], v[162:165], v[208:211], v[74:77]
	s_barrier
	s_setprio 0
	s_add_i32 s1, s51, s31
	s_mov_b32 m0, s1
	ds_read_b128 v[178:181], v144 offset:16384
	ds_read_b128 v[182:185], v144 offset:17408
	ds_read_b128 v[192:195], v144 offset:18432
	ds_read_b128 v[196:199], v144 offset:19456
	ds_read_b128 v[200:203], v144 offset:20480
	ds_read_b128 v[204:207], v144 offset:21504
	ds_read_b128 v[208:211], v144 offset:22528
	ds_read_b128 v[212:215], v144 offset:23552
	global_load_lds_dwordx4 v186, s[24:25]
	s_add_i32 m0, s1, 0x2000
	s_add_u32 s52, s24, 0x80000
	s_addc_u32 s53, s25, 0
	s_add_i32 s0, s0, s31
	global_load_lds_dwordx4 v130, s[24:25]
	s_mov_b32 m0, s0
	s_nop 0
	global_load_lds_dwordx4 v186, s[52:53]
	s_add_i32 m0, s0, 0x2000
	s_nop 0
	global_load_lds_dwordx4 v130, s[52:53]
	s_mov_b32 m0, s35
	s_nop 0
	global_load_lds_dwordx4 v134, s[26:27]
	s_mov_b32 m0, s36
	s_nop 0
	global_load_lds_dwordx4 v132, s[26:27]
	s_waitcnt vmcnt(8)
	s_waitcnt lgkmcnt(0)
	s_setprio 1
	s_barrier

	v_mfma_f32_16x16x32_bf16 v[62:65], v[146:149], v[178:181], v[62:65]
	v_mfma_f32_16x16x32_bf16 v[62:65], v[150:153], v[182:185], v[62:65]
	v_mfma_f32_16x16x32_bf16 v[54:57], v[158:161], v[182:185], v[54:57]
	v_mfma_f32_16x16x32_bf16 v[54:57], v[154:157], v[178:181], v[54:57]
	v_mfma_f32_16x16x32_bf16 v[38:41], v[154:157], v[192:195], v[38:41]
	v_mfma_f32_16x16x32_bf16 v[38:41], v[158:161], v[196:199], v[38:41]
	v_mfma_f32_16x16x32_bf16 v[46:49], v[150:153], v[196:199], v[46:49]
	v_mfma_f32_16x16x32_bf16 v[46:49], v[146:149], v[192:195], v[46:49]
	v_mfma_f32_16x16x32_bf16 v[30:33], v[146:149], v[200:203], v[30:33]
	v_mfma_f32_16x16x32_bf16 v[30:33], v[150:153], v[204:207], v[30:33]
	v_mfma_f32_16x16x32_bf16 v[22:25], v[158:161], v[204:207], v[22:25]
	v_mfma_f32_16x16x32_bf16 v[22:25], v[154:157], v[200:203], v[22:25]
	v_mfma_f32_16x16x32_bf16 v[6:9], v[154:157], v[208:211], v[6:9]
	v_mfma_f32_16x16x32_bf16 v[6:9], v[158:161], v[212:215], v[6:9]
	v_mfma_f32_16x16x32_bf16 v[14:17], v[150:153], v[212:215], v[14:17]
	v_mfma_f32_16x16x32_bf16 v[14:17], v[146:149], v[208:211], v[14:17]


	v_mfma_f32_16x16x32_bf16 v[58:61], v[162:165], v[178:181], v[58:61]
	v_mfma_f32_16x16x32_bf16 v[58:61], v[166:169], v[182:185], v[58:61]
	v_mfma_f32_16x16x32_bf16 v[50:53], v[174:177], v[182:185], v[50:53]
	v_mfma_f32_16x16x32_bf16 v[50:53], v[170:173], v[178:181], v[50:53]
	v_mfma_f32_16x16x32_bf16 v[34:37], v[170:173], v[192:195], v[34:37]
	v_mfma_f32_16x16x32_bf16 v[34:37], v[174:177], v[196:199], v[34:37]
	v_mfma_f32_16x16x32_bf16 v[42:45], v[166:169], v[196:199], v[42:45]
	v_mfma_f32_16x16x32_bf16 v[42:45], v[162:165], v[192:195], v[42:45]
	v_mfma_f32_16x16x32_bf16 v[26:29], v[162:165], v[200:203], v[26:29]
	v_mfma_f32_16x16x32_bf16 v[26:29], v[166:169], v[204:207], v[26:29]
	v_mfma_f32_16x16x32_bf16 v[18:21], v[174:177], v[204:207], v[18:21]
	v_mfma_f32_16x16x32_bf16 v[18:21], v[170:173], v[200:203], v[18:21]
	v_mfma_f32_16x16x32_bf16 v[2:5], v[170:173], v[208:211], v[2:5]
	v_mfma_f32_16x16x32_bf16 v[2:5], v[174:177], v[212:215], v[2:5]
	v_mfma_f32_16x16x32_bf16 v[10:13], v[166:169], v[212:215], v[10:13]
	v_mfma_f32_16x16x32_bf16 v[10:13], v[162:165], v[208:211], v[10:13]
	s_barrier
	s_setprio 0
	s_add_i32 s0, 0, 0x18000
	v_add_u32_e32 v145, s0, v143
	s_add_i32 s1, 0, 0x1c000
	ds_read_b128 v[146:149], v145
	ds_read_b128 v[150:153], v145 offset:1024
	ds_read_b128 v[154:157], v145 offset:2048
	ds_read_b128 v[158:161], v145 offset:3072
	v_add_u32_e32 v145, s1, v143
	ds_read_b128 v[162:165], v145
	ds_read_b128 v[166:169], v145 offset:1024
	ds_read_b128 v[170:173], v145 offset:2048
	ds_read_b128 v[174:177], v145 offset:3072
	s_add_u32 s26, s26, 0x80000
	s_addc_u32 s27, s27, 0
	s_mov_b32 m0, s37
	ds_read_b128 v[178:181], v144 offset:32768
	ds_read_b128 v[182:185], v144 offset:33792
	ds_read_b128 v[192:195], v144 offset:34816
	ds_read_b128 v[196:199], v144 offset:35840
	ds_read_b128 v[200:203], v144 offset:36864
	ds_read_b128 v[204:207], v144 offset:37888
	ds_read_b128 v[208:211], v144 offset:38912
	ds_read_b128 v[212:215], v144 offset:39936
	global_load_lds_dwordx4 v134, s[26:27]
	s_mov_b32 m0, s38
	s_nop 0
	global_load_lds_dwordx4 v132, s[26:27]
	s_waitcnt vmcnt(8)
	s_waitcnt lgkmcnt(0)
	s_setprio 1
	s_barrier

	v_mfma_f32_16x16x32_bf16 v[126:129], v[146:149], v[178:181], v[126:129]
	v_mfma_f32_16x16x32_bf16 v[126:129], v[150:153], v[182:185], v[126:129]
	v_mfma_f32_16x16x32_bf16 v[118:121], v[158:161], v[182:185], v[118:121]
	v_mfma_f32_16x16x32_bf16 v[118:121], v[154:157], v[178:181], v[118:121]
	v_mfma_f32_16x16x32_bf16 v[102:105], v[154:157], v[192:195], v[102:105]
	v_mfma_f32_16x16x32_bf16 v[102:105], v[158:161], v[196:199], v[102:105]
	v_mfma_f32_16x16x32_bf16 v[110:113], v[150:153], v[196:199], v[110:113]
	v_mfma_f32_16x16x32_bf16 v[110:113], v[146:149], v[192:195], v[110:113]
	v_mfma_f32_16x16x32_bf16 v[94:97], v[146:149], v[200:203], v[94:97]
	v_mfma_f32_16x16x32_bf16 v[94:97], v[150:153], v[204:207], v[94:97]
	v_mfma_f32_16x16x32_bf16 v[86:89], v[158:161], v[204:207], v[86:89]
	v_mfma_f32_16x16x32_bf16 v[86:89], v[154:157], v[200:203], v[86:89]
	v_mfma_f32_16x16x32_bf16 v[70:73], v[154:157], v[208:211], v[70:73]
	v_mfma_f32_16x16x32_bf16 v[70:73], v[158:161], v[212:215], v[70:73]
	v_mfma_f32_16x16x32_bf16 v[78:81], v[150:153], v[212:215], v[78:81]
	v_mfma_f32_16x16x32_bf16 v[78:81], v[146:149], v[208:211], v[78:81]


	v_mfma_f32_16x16x32_bf16 v[122:125], v[162:165], v[178:181], v[122:125]
	v_mfma_f32_16x16x32_bf16 v[122:125], v[166:169], v[182:185], v[122:125]
	v_mfma_f32_16x16x32_bf16 v[114:117], v[174:177], v[182:185], v[114:117]
	v_mfma_f32_16x16x32_bf16 v[114:117], v[170:173], v[178:181], v[114:117]
	v_mfma_f32_16x16x32_bf16 v[98:101], v[170:173], v[192:195], v[98:101]
	v_mfma_f32_16x16x32_bf16 v[98:101], v[174:177], v[196:199], v[98:101]
	v_mfma_f32_16x16x32_bf16 v[106:109], v[166:169], v[196:199], v[106:109]
	v_mfma_f32_16x16x32_bf16 v[106:109], v[162:165], v[192:195], v[106:109]
	v_mfma_f32_16x16x32_bf16 v[90:93], v[162:165], v[200:203], v[90:93]
	v_mfma_f32_16x16x32_bf16 v[90:93], v[166:169], v[204:207], v[90:93]
	v_mfma_f32_16x16x32_bf16 v[82:85], v[174:177], v[204:207], v[82:85]
	v_mfma_f32_16x16x32_bf16 v[82:85], v[170:173], v[200:203], v[82:85]
	v_mfma_f32_16x16x32_bf16 v[66:69], v[170:173], v[208:211], v[66:69]
	v_mfma_f32_16x16x32_bf16 v[66:69], v[174:177], v[212:215], v[66:69]
	v_mfma_f32_16x16x32_bf16 v[74:77], v[166:169], v[212:215], v[74:77]
	v_mfma_f32_16x16x32_bf16 v[74:77], v[162:165], v[208:211], v[74:77]
	s_barrier
	s_setprio 0
	s_add_i32 s0, s0, s31
	s_mov_b32 m0, s0
	ds_read_b128 v[178:181], v144 offset:49152
	ds_read_b128 v[182:185], v144 offset:50176
	ds_read_b128 v[192:195], v144 offset:51200
	ds_read_b128 v[196:199], v144 offset:52224
	ds_read_b128 v[200:203], v144 offset:53248
	ds_read_b128 v[204:207], v144 offset:54272
	ds_read_b128 v[208:211], v144 offset:55296
	ds_read_b128 v[212:215], v144 offset:56320
	s_add_u32 s100, s24, 0x80
	s_addc_u32 s101, s25, 0
	global_load_lds_dwordx4 v186, s[100:101]
	s_add_i32 m0, s0, 0x2000
	s_add_u32 s24, s24, 0x80080
	s_addc_u32 s25, s25, 0
	s_add_i32 s0, s1, s31
	s_add_u32 s100, s24, 0xfff80000
	s_addc_u32 s101, s25, -1
	global_load_lds_dwordx4 v130, s[100:101]
	s_mov_b32 m0, s0
	s_nop 0
	global_load_lds_dwordx4 v186, s[24:25]
	s_add_i32 m0, s0, 0x2000
	s_nop 0
	global_load_lds_dwordx4 v130, s[24:25]
	s_mov_b32 m0, s39
	s_nop 0
	s_add_u32 s100, s26, 0xfff80080
	s_addc_u32 s101, s27, -1
	global_load_lds_dwordx4 v134, s[100:101]
	s_mov_b32 m0, s40
	s_nop 0
	s_add_u32 s100, s26, 0xfff80080
	s_addc_u32 s101, s27, -1
	global_load_lds_dwordx4 v132, s[100:101]
	s_waitcnt vmcnt(8)
	s_waitcnt lgkmcnt(0)
	s_setprio 1
	s_barrier

	v_mfma_f32_16x16x32_bf16 v[62:65], v[146:149], v[178:181], v[62:65]
	v_mfma_f32_16x16x32_bf16 v[62:65], v[150:153], v[182:185], v[62:65]
	v_mfma_f32_16x16x32_bf16 v[54:57], v[158:161], v[182:185], v[54:57]
	v_mfma_f32_16x16x32_bf16 v[54:57], v[154:157], v[178:181], v[54:57]
	v_mfma_f32_16x16x32_bf16 v[38:41], v[154:157], v[192:195], v[38:41]
	v_mfma_f32_16x16x32_bf16 v[38:41], v[158:161], v[196:199], v[38:41]
	v_mfma_f32_16x16x32_bf16 v[46:49], v[150:153], v[196:199], v[46:49]
	v_mfma_f32_16x16x32_bf16 v[46:49], v[146:149], v[192:195], v[46:49]
	v_mfma_f32_16x16x32_bf16 v[30:33], v[146:149], v[200:203], v[30:33]
	v_mfma_f32_16x16x32_bf16 v[30:33], v[150:153], v[204:207], v[30:33]
	v_mfma_f32_16x16x32_bf16 v[22:25], v[158:161], v[204:207], v[22:25]
	v_mfma_f32_16x16x32_bf16 v[22:25], v[154:157], v[200:203], v[22:25]
	v_mfma_f32_16x16x32_bf16 v[6:9], v[154:157], v[208:211], v[6:9]
	v_mfma_f32_16x16x32_bf16 v[6:9], v[158:161], v[212:215], v[6:9]
	v_mfma_f32_16x16x32_bf16 v[14:17], v[150:153], v[212:215], v[14:17]
	v_mfma_f32_16x16x32_bf16 v[14:17], v[146:149], v[208:211], v[14:17]


	v_mfma_f32_16x16x32_bf16 v[58:61], v[162:165], v[178:181], v[58:61]
	v_mfma_f32_16x16x32_bf16 v[58:61], v[166:169], v[182:185], v[58:61]
	v_mfma_f32_16x16x32_bf16 v[50:53], v[174:177], v[182:185], v[50:53]
	v_mfma_f32_16x16x32_bf16 v[50:53], v[170:173], v[178:181], v[50:53]
	v_mfma_f32_16x16x32_bf16 v[34:37], v[170:173], v[192:195], v[34:37]
	v_mfma_f32_16x16x32_bf16 v[34:37], v[174:177], v[196:199], v[34:37]
	v_mfma_f32_16x16x32_bf16 v[42:45], v[166:169], v[196:199], v[42:45]
	v_mfma_f32_16x16x32_bf16 v[42:45], v[162:165], v[192:195], v[42:45]
	v_mfma_f32_16x16x32_bf16 v[26:29], v[162:165], v[200:203], v[26:29]
	v_mfma_f32_16x16x32_bf16 v[26:29], v[166:169], v[204:207], v[26:29]
	v_mfma_f32_16x16x32_bf16 v[18:21], v[174:177], v[204:207], v[18:21]
	v_mfma_f32_16x16x32_bf16 v[18:21], v[170:173], v[200:203], v[18:21]
	v_mfma_f32_16x16x32_bf16 v[2:5], v[170:173], v[208:211], v[2:5]
	v_mfma_f32_16x16x32_bf16 v[2:5], v[174:177], v[212:215], v[2:5]
	v_mfma_f32_16x16x32_bf16 v[10:13], v[166:169], v[212:215], v[10:13]
	v_mfma_f32_16x16x32_bf16 v[10:13], v[162:165], v[208:211], v[10:13]
	s_barrier
	s_setprio 0
	s_add_i32 s50, s50, 2
	s_add_u32 s22, s22, 0x100
	s_addc_u32 s23, s23, 0
	s_add_u32 s48, s48, 0x100
	s_addc_u32 s49, s49, 0
	s_cmp_gt_u32 s50, 29
	s_cbranch_scc0 .LBB0_159


.LBB0_162:
	v_mov_b32_e32 v140, v1
	v_mov_b32_e32 v141, v142
	v_pk_mul_f32 v[124:125], v[128:129], v[124:125]
	v_add_u32_e32 v145, s43, v140
	v_lshl_add_u32 v146, v145, 2, 0
	v_add_u32_e32 v146, 0x20400, v146
	ds_read_b32 v147, v146
	v_pk_mul_f32 v[122:123], v[126:127], v[122:123]
	v_pk_mul_f32 v[116:117], v[120:121], v[116:117]
	v_pk_mul_f32 v[114:115], v[118:119], v[114:115]
	s_lshl_b32 s0, s20, 8
	s_waitcnt lgkmcnt(0)
	v_mul_f32_e32 v148, 0xbfb8aa3b, v147
	v_pk_mul_f32 v[128:129], v[128:129], v[148:149] op_sel_hi:[1,0]
	v_pk_mul_f32 v[126:127], v[126:127], v[148:149] op_sel_hi:[1,0]
	v_pk_mul_f32 v[120:121], v[120:121], v[148:149] op_sel_hi:[1,0]
	v_exp_f32_e32 v126, v126
	v_exp_f32_e32 v127, v127
	v_exp_f32_e32 v128, v128
	v_exp_f32_e32 v129, v129
	v_pk_mul_f32 v[118:119], v[118:119], v[148:149] op_sel_hi:[1,0]
	v_exp_f32_e32 v120, v120
	v_exp_f32_e32 v121, v121
	v_exp_f32_e32 v118, v118
	v_exp_f32_e32 v119, v119
	v_pk_add_f32 v[128:129], v[128:129], 1.0 op_sel_hi:[1,0]
	v_pk_add_f32 v[126:127], v[126:127], 1.0 op_sel_hi:[1,0]
	v_pk_add_f32 v[120:121], v[120:121], 1.0 op_sel_hi:[1,0]
	s_mul_i32 s1, s20, 0x2c0000
	v_rcp_f32_e32 v126, v126
	v_rcp_f32_e32 v127, v127
	v_rcp_f32_e32 v128, v128
	v_rcp_f32_e32 v129, v129
	v_pk_add_f32 v[118:119], v[118:119], 1.0 op_sel_hi:[1,0]
	v_rcp_f32_e32 v120, v120
	v_rcp_f32_e32 v121, v121
	s_mul_hi_i32 s0, s0, 0x2c00
	s_add_u32 s1, s41, s1
	v_rcp_f32_e32 v118, v118
	v_rcp_f32_e32 v119, v119
	s_addc_u32 s0, s42, s0
	s_lshl_b32 s20, s21, 7
	s_ashr_i32 s21, s20, 31
	v_mul_f32_e32 v150, v147, v147
	s_lshl_b64 s[20:21], s[20:21], 1
	v_pk_mul_f32 v[128:129], v[150:151], v[128:129] op_sel_hi:[0,1]
	v_pk_mul_f32 v[126:127], v[150:151], v[126:127] op_sel_hi:[0,1]
	v_pk_mul_f32 v[120:121], v[150:151], v[120:121] op_sel_hi:[0,1]
	s_add_u32 s1, s1, s20
	v_pk_mul_f32 v[124:125], v[124:125], v[128:129]
	v_pk_mul_f32 v[122:123], v[122:123], v[126:127]
	v_pk_mul_f32 v[118:119], v[150:151], v[118:119] op_sel_hi:[0,1]
	v_pk_mul_f32 v[116:117], v[116:117], v[120:121]
	s_addc_u32 s0, s0, s21
	v_cvt_pk_bf16_f32 v122, v122, v123
	v_cvt_pk_bf16_f32 v123, v124, v125
	v_pk_mul_f32 v[114:115], v[114:115], v[118:119]
	s_add_u32 s20, s1, s45
	v_cvt_pk_bf16_f32 v124, v114, v115
	v_cvt_pk_bf16_f32 v125, v116, v117
	ds_read_b32 v116, v146 offset:64
	v_lshlrev_b32_e32 v140, 3, v141
	s_addc_u32 s21, s0, 0
	v_ashrrev_i32_e32 v141, 31, v140
	v_lshl_add_u64 v[140:141], v[140:141], 1, s[20:21]
	s_movk_i32 s0, 0x2c00
	v_mad_i64_i32 v[114:115], s[20:21], v145, s0, v[140:141]
	global_store_dwordx4 v[114:115], v[122:125], off
	v_add_u32_e32 v115, 16, v145
	s_waitcnt lgkmcnt(0)
	v_mul_f32_e32 v114, 0xbfb8aa3b, v116
	v_pk_mul_f32 v[108:109], v[112:113], v[108:109]
	v_pk_mul_f32 v[106:107], v[110:111], v[106:107]
	v_pk_mul_f32 v[112:113], v[112:113], v[114:115] op_sel_hi:[1,0]
	v_pk_mul_f32 v[110:111], v[110:111], v[114:115] op_sel_hi:[1,0]
	v_pk_mul_f32 v[100:101], v[104:105], v[100:101]
	v_pk_mul_f32 v[104:105], v[104:105], v[114:115] op_sel_hi:[1,0]
	v_exp_f32_e32 v110, v110
	v_exp_f32_e32 v111, v111
	v_exp_f32_e32 v112, v112
	v_exp_f32_e32 v113, v113
	v_pk_mul_f32 v[98:99], v[102:103], v[98:99]
	v_pk_mul_f32 v[102:103], v[102:103], v[114:115] op_sel_hi:[1,0]
	v_exp_f32_e32 v104, v104
	v_exp_f32_e32 v105, v105
	v_exp_f32_e32 v102, v102
	v_exp_f32_e32 v103, v103
	v_pk_add_f32 v[112:113], v[112:113], 1.0 op_sel_hi:[1,0]
	v_pk_add_f32 v[110:111], v[110:111], 1.0 op_sel_hi:[1,0]
	v_pk_add_f32 v[104:105], v[104:105], 1.0 op_sel_hi:[1,0]
	v_rcp_f32_e32 v110, v110
	v_rcp_f32_e32 v111, v111
	v_rcp_f32_e32 v112, v112
	v_rcp_f32_e32 v113, v113
	v_pk_add_f32 v[102:103], v[102:103], 1.0 op_sel_hi:[1,0]
	v_rcp_f32_e32 v104, v104
	v_rcp_f32_e32 v105, v105
	v_rcp_f32_e32 v102, v102
	v_rcp_f32_e32 v103, v103
	v_mul_f32_e32 v116, v116, v116
	v_pk_mul_f32 v[112:113], v[116:117], v[112:113] op_sel_hi:[0,1]
	v_pk_mul_f32 v[110:111], v[116:117], v[110:111] op_sel_hi:[0,1]
	v_pk_mul_f32 v[104:105], v[116:117], v[104:105] op_sel_hi:[0,1]
	v_pk_mul_f32 v[108:109], v[108:109], v[112:113]
	v_pk_mul_f32 v[106:107], v[106:107], v[110:111]
	v_pk_mul_f32 v[102:103], v[116:117], v[102:103] op_sel_hi:[0,1]
	v_pk_mul_f32 v[100:101], v[100:101], v[104:105]
	v_cvt_pk_bf16_f32 v106, v106, v107
	v_cvt_pk_bf16_f32 v107, v108, v109
	v_pk_mul_f32 v[98:99], v[98:99], v[102:103]
	v_pk_mul_f32 v[92:93], v[96:97], v[92:93]
	v_cvt_pk_bf16_f32 v108, v98, v99
	v_cvt_pk_bf16_f32 v109, v100, v101
	ds_read_b32 v100, v146 offset:128
	v_mad_i64_i32 v[98:99], s[20:21], v115, s0, v[140:141]
	global_store_dwordx4 v[98:99], v[106:109], off
	s_and_b64 vcc, exec, s[10:11]
	s_cbranch_vccz .Lep_a0
	s_barrier
.Lep_a0:
	v_add_u32_e32 v99, 32, v145
	s_waitcnt lgkmcnt(0)
	v_mul_f32_e32 v98, 0xbfb8aa3b, v100
	v_pk_mul_f32 v[90:91], v[94:95], v[90:91]
	v_pk_mul_f32 v[96:97], v[96:97], v[98:99] op_sel_hi:[1,0]
	v_pk_mul_f32 v[94:95], v[94:95], v[98:99] op_sel_hi:[1,0]
	v_pk_mul_f32 v[84:85], v[88:89], v[84:85]
	v_pk_mul_f32 v[88:89], v[88:89], v[98:99] op_sel_hi:[1,0]
	v_exp_f32_e32 v94, v94
	v_exp_f32_e32 v95, v95
	v_exp_f32_e32 v96, v96
	v_exp_f32_e32 v97, v97
	v_pk_mul_f32 v[82:83], v[86:87], v[82:83]
	v_pk_mul_f32 v[86:87], v[86:87], v[98:99] op_sel_hi:[1,0]
	v_exp_f32_e32 v88, v88
	v_exp_f32_e32 v89, v89
	v_exp_f32_e32 v86, v86
	v_exp_f32_e32 v87, v87
	v_pk_add_f32 v[96:97], v[96:97], 1.0 op_sel_hi:[1,0]
	v_pk_add_f32 v[94:95], v[94:95], 1.0 op_sel_hi:[1,0]
	v_pk_add_f32 v[88:89], v[88:89], 1.0 op_sel_hi:[1,0]
	v_rcp_f32_e32 v94, v94
	v_rcp_f32_e32 v95, v95
	v_rcp_f32_e32 v96, v96
	v_rcp_f32_e32 v97, v97
	v_pk_add_f32 v[86:87], v[86:87], 1.0 op_sel_hi:[1,0]
	v_rcp_f32_e32 v88, v88
	v_rcp_f32_e32 v89, v89
	v_rcp_f32_e32 v86, v86
	v_rcp_f32_e32 v87, v87
	v_mul_f32_e32 v100, v100, v100
	v_pk_mul_f32 v[96:97], v[100:101], v[96:97] op_sel_hi:[0,1]
	v_pk_mul_f32 v[94:95], v[100:101], v[94:95] op_sel_hi:[0,1]
	v_pk_mul_f32 v[88:89], v[100:101], v[88:89] op_sel_hi:[0,1]
	v_pk_mul_f32 v[92:93], v[92:93], v[96:97]
	v_pk_mul_f32 v[90:91], v[90:91], v[94:95]
	v_pk_mul_f32 v[86:87], v[100:101], v[86:87] op_sel_hi:[0,1]
	v_pk_mul_f32 v[84:85], v[84:85], v[88:89]
	v_cvt_pk_bf16_f32 v90, v90, v91
	v_cvt_pk_bf16_f32 v91, v92, v93
	v_pk_mul_f32 v[82:83], v[82:83], v[86:87]
	v_pk_mul_f32 v[76:77], v[80:81], v[76:77]
	v_cvt_pk_bf16_f32 v92, v82, v83
	v_cvt_pk_bf16_f32 v93, v84, v85
	ds_read_b32 v84, v146 offset:192
	v_mad_i64_i32 v[82:83], s[20:21], v99, s0, v[140:141]
	global_store_dwordx4 v[82:83], v[90:93], off
	v_add_u32_e32 v83, 48, v145
	s_waitcnt lgkmcnt(0)
	v_mul_f32_e32 v82, 0xbfb8aa3b, v84
	v_pk_mul_f32 v[74:75], v[78:79], v[74:75]
	v_pk_mul_f32 v[80:81], v[80:81], v[82:83] op_sel_hi:[1,0]
	v_pk_mul_f32 v[78:79], v[78:79], v[82:83] op_sel_hi:[1,0]
	v_pk_mul_f32 v[68:69], v[72:73], v[68:69]
	v_pk_mul_f32 v[72:73], v[72:73], v[82:83] op_sel_hi:[1,0]
	v_exp_f32_e32 v78, v78
	v_exp_f32_e32 v79, v79
	v_exp_f32_e32 v80, v80
	v_exp_f32_e32 v81, v81
	v_pk_mul_f32 v[66:67], v[70:71], v[66:67]
	v_pk_mul_f32 v[70:71], v[70:71], v[82:83] op_sel_hi:[1,0]
	v_exp_f32_e32 v72, v72
	v_exp_f32_e32 v73, v73
	v_exp_f32_e32 v70, v70
	v_exp_f32_e32 v71, v71
	v_pk_add_f32 v[80:81], v[80:81], 1.0 op_sel_hi:[1,0]
	v_pk_add_f32 v[78:79], v[78:79], 1.0 op_sel_hi:[1,0]
	v_pk_add_f32 v[72:73], v[72:73], 1.0 op_sel_hi:[1,0]
	v_rcp_f32_e32 v78, v78
	v_rcp_f32_e32 v79, v79
	v_rcp_f32_e32 v80, v80
	v_rcp_f32_e32 v81, v81
	v_pk_add_f32 v[70:71], v[70:71], 1.0 op_sel_hi:[1,0]
	v_rcp_f32_e32 v72, v72
	v_rcp_f32_e32 v73, v73
	v_rcp_f32_e32 v70, v70
	v_rcp_f32_e32 v71, v71
	v_mul_f32_e32 v84, v84, v84
	v_pk_mul_f32 v[80:81], v[84:85], v[80:81] op_sel_hi:[0,1]
	v_pk_mul_f32 v[78:79], v[84:85], v[78:79] op_sel_hi:[0,1]
	v_pk_mul_f32 v[72:73], v[84:85], v[72:73] op_sel_hi:[0,1]
	v_pk_mul_f32 v[76:77], v[76:77], v[80:81]
	v_pk_mul_f32 v[74:75], v[74:75], v[78:79]
	v_pk_mul_f32 v[70:71], v[84:85], v[70:71] op_sel_hi:[0,1]
	v_pk_mul_f32 v[68:69], v[68:69], v[72:73]
	v_cvt_pk_bf16_f32 v74, v74, v75
	v_cvt_pk_bf16_f32 v75, v76, v77
	v_pk_mul_f32 v[66:67], v[66:67], v[70:71]
	v_pk_mul_f32 v[60:61], v[64:65], v[60:61]
	v_cvt_pk_bf16_f32 v76, v66, v67
	v_cvt_pk_bf16_f32 v77, v68, v69
	ds_read_b32 v68, v146 offset:512
	v_mad_i64_i32 v[66:67], s[20:21], v83, s0, v[140:141]
	global_store_dwordx4 v[66:67], v[74:77], off
	v_add_u32_e32 v67, 0x80, v145
	s_waitcnt lgkmcnt(0)
	v_mul_f32_e32 v66, 0xbfb8aa3b, v68
	v_pk_mul_f32 v[58:59], v[62:63], v[58:59]
	v_pk_mul_f32 v[64:65], v[64:65], v[66:67] op_sel_hi:[1,0]
	v_pk_mul_f32 v[62:63], v[62:63], v[66:67] op_sel_hi:[1,0]
	v_pk_mul_f32 v[52:53], v[56:57], v[52:53]
	v_pk_mul_f32 v[56:57], v[56:57], v[66:67] op_sel_hi:[1,0]
	v_exp_f32_e32 v62, v62
	v_exp_f32_e32 v63, v63
	v_exp_f32_e32 v64, v64
	v_exp_f32_e32 v65, v65
	v_pk_mul_f32 v[50:51], v[54:55], v[50:51]
	v_pk_mul_f32 v[54:55], v[54:55], v[66:67] op_sel_hi:[1,0]
	v_exp_f32_e32 v56, v56
	v_exp_f32_e32 v57, v57
	v_exp_f32_e32 v54, v54
	v_exp_f32_e32 v55, v55
	v_pk_add_f32 v[64:65], v[64:65], 1.0 op_sel_hi:[1,0]
	v_pk_add_f32 v[62:63], v[62:63], 1.0 op_sel_hi:[1,0]
	v_pk_add_f32 v[56:57], v[56:57], 1.0 op_sel_hi:[1,0]
	v_rcp_f32_e32 v62, v62
	v_rcp_f32_e32 v63, v63
	v_rcp_f32_e32 v64, v64
	v_rcp_f32_e32 v65, v65
	v_pk_add_f32 v[54:55], v[54:55], 1.0 op_sel_hi:[1,0]
	v_rcp_f32_e32 v56, v56
	v_rcp_f32_e32 v57, v57
	v_rcp_f32_e32 v54, v54
	v_rcp_f32_e32 v55, v55
	v_mul_f32_e32 v68, v68, v68
	v_pk_mul_f32 v[64:65], v[68:69], v[64:65] op_sel_hi:[0,1]
	v_pk_mul_f32 v[62:63], v[68:69], v[62:63] op_sel_hi:[0,1]
	v_pk_mul_f32 v[56:57], v[68:69], v[56:57] op_sel_hi:[0,1]
	v_pk_mul_f32 v[60:61], v[60:61], v[64:65]
	v_pk_mul_f32 v[58:59], v[58:59], v[62:63]
	v_pk_mul_f32 v[54:55], v[68:69], v[54:55] op_sel_hi:[0,1]
	v_pk_mul_f32 v[52:53], v[52:53], v[56:57]
	v_cvt_pk_bf16_f32 v58, v58, v59
	v_cvt_pk_bf16_f32 v59, v60, v61
	v_pk_mul_f32 v[50:51], v[50:51], v[54:55]
	v_pk_mul_f32 v[44:45], v[48:49], v[44:45]
	v_cvt_pk_bf16_f32 v60, v50, v51
	v_cvt_pk_bf16_f32 v61, v52, v53
	ds_read_b32 v52, v146 offset:576
	v_mad_i64_i32 v[50:51], s[20:21], v67, s0, v[140:141]
	global_store_dwordx4 v[50:51], v[58:61], off
	v_add_u32_e32 v51, 0x90, v145
	s_waitcnt lgkmcnt(0)
	v_mul_f32_e32 v50, 0xbfb8aa3b, v52
	v_pk_mul_f32 v[42:43], v[46:47], v[42:43]
	v_pk_mul_f32 v[48:49], v[48:49], v[50:51] op_sel_hi:[1,0]
	v_pk_mul_f32 v[46:47], v[46:47], v[50:51] op_sel_hi:[1,0]
	v_pk_mul_f32 v[36:37], v[40:41], v[36:37]
	v_pk_mul_f32 v[40:41], v[40:41], v[50:51] op_sel_hi:[1,0]
	v_exp_f32_e32 v46, v46
	v_exp_f32_e32 v47, v47
	v_exp_f32_e32 v48, v48
	v_exp_f32_e32 v49, v49
	v_pk_mul_f32 v[34:35], v[38:39], v[34:35]
	v_pk_mul_f32 v[38:39], v[38:39], v[50:51] op_sel_hi:[1,0]
	v_exp_f32_e32 v40, v40
	v_exp_f32_e32 v41, v41
	v_exp_f32_e32 v38, v38
	v_exp_f32_e32 v39, v39
	v_pk_add_f32 v[48:49], v[48:49], 1.0 op_sel_hi:[1,0]
	v_pk_add_f32 v[46:47], v[46:47], 1.0 op_sel_hi:[1,0]
	v_pk_add_f32 v[40:41], v[40:41], 1.0 op_sel_hi:[1,0]
	v_rcp_f32_e32 v46, v46
	v_rcp_f32_e32 v47, v47
	v_rcp_f32_e32 v48, v48
	v_rcp_f32_e32 v49, v49
	v_pk_add_f32 v[38:39], v[38:39], 1.0 op_sel_hi:[1,0]
	v_rcp_f32_e32 v40, v40
	v_rcp_f32_e32 v41, v41
	v_rcp_f32_e32 v38, v38
	v_rcp_f32_e32 v39, v39
	v_mul_f32_e32 v52, v52, v52
	v_pk_mul_f32 v[48:49], v[52:53], v[48:49] op_sel_hi:[0,1]
	v_pk_mul_f32 v[46:47], v[52:53], v[46:47] op_sel_hi:[0,1]
	v_pk_mul_f32 v[40:41], v[52:53], v[40:41] op_sel_hi:[0,1]
	v_pk_mul_f32 v[44:45], v[44:45], v[48:49]
	v_pk_mul_f32 v[42:43], v[42:43], v[46:47]
	v_pk_mul_f32 v[38:39], v[52:53], v[38:39] op_sel_hi:[0,1]
	v_pk_mul_f32 v[36:37], v[36:37], v[40:41]
	v_cvt_pk_bf16_f32 v42, v42, v43
	v_cvt_pk_bf16_f32 v43, v44, v45
	v_pk_mul_f32 v[34:35], v[34:35], v[38:39]
	v_pk_mul_f32 v[28:29], v[32:33], v[28:29]
	v_cvt_pk_bf16_f32 v44, v34, v35
	v_cvt_pk_bf16_f32 v45, v36, v37
	ds_read_b32 v36, v146 offset:640
	v_mad_i64_i32 v[34:35], s[20:21], v51, s0, v[140:141]
	global_store_dwordx4 v[34:35], v[42:45], off
	v_add_u32_e32 v35, 0xa0, v145
	s_waitcnt lgkmcnt(0)
	v_mul_f32_e32 v34, 0xbfb8aa3b, v36
	v_pk_mul_f32 v[26:27], v[30:31], v[26:27]
	v_pk_mul_f32 v[32:33], v[32:33], v[34:35] op_sel_hi:[1,0]
	v_pk_mul_f32 v[30:31], v[30:31], v[34:35] op_sel_hi:[1,0]
	v_pk_mul_f32 v[20:21], v[24:25], v[20:21]
	v_pk_mul_f32 v[24:25], v[24:25], v[34:35] op_sel_hi:[1,0]
	v_exp_f32_e32 v30, v30
	v_exp_f32_e32 v31, v31
	v_exp_f32_e32 v32, v32
	v_exp_f32_e32 v33, v33
	v_pk_mul_f32 v[18:19], v[22:23], v[18:19]
	v_pk_mul_f32 v[22:23], v[22:23], v[34:35] op_sel_hi:[1,0]
	v_exp_f32_e32 v24, v24
	v_exp_f32_e32 v25, v25
	v_exp_f32_e32 v22, v22
	v_exp_f32_e32 v23, v23
	v_pk_add_f32 v[32:33], v[32:33], 1.0 op_sel_hi:[1,0]
	v_pk_add_f32 v[30:31], v[30:31], 1.0 op_sel_hi:[1,0]
	v_pk_add_f32 v[24:25], v[24:25], 1.0 op_sel_hi:[1,0]
	v_rcp_f32_e32 v30, v30
	v_rcp_f32_e32 v31, v31
	v_rcp_f32_e32 v32, v32
	v_rcp_f32_e32 v33, v33
	v_pk_add_f32 v[22:23], v[22:23], 1.0 op_sel_hi:[1,0]
	v_rcp_f32_e32 v24, v24
	v_rcp_f32_e32 v25, v25
	v_rcp_f32_e32 v22, v22
	v_rcp_f32_e32 v23, v23
	v_mul_f32_e32 v36, v36, v36
	v_pk_mul_f32 v[32:33], v[36:37], v[32:33] op_sel_hi:[0,1]
	v_pk_mul_f32 v[30:31], v[36:37], v[30:31] op_sel_hi:[0,1]
	v_pk_mul_f32 v[24:25], v[36:37], v[24:25] op_sel_hi:[0,1]
	v_pk_mul_f32 v[28:29], v[28:29], v[32:33]
	v_pk_mul_f32 v[26:27], v[26:27], v[30:31]
	v_pk_mul_f32 v[22:23], v[36:37], v[22:23] op_sel_hi:[0,1]
	v_pk_mul_f32 v[20:21], v[20:21], v[24:25]
	v_cvt_pk_bf16_f32 v26, v26, v27
	v_cvt_pk_bf16_f32 v27, v28, v29
	v_pk_mul_f32 v[18:19], v[18:19], v[22:23]
	v_pk_mul_f32 v[12:13], v[16:17], v[12:13]
	v_cvt_pk_bf16_f32 v28, v18, v19
	v_cvt_pk_bf16_f32 v29, v20, v21
	ds_read_b32 v20, v146 offset:704
	v_mad_i64_i32 v[18:19], s[20:21], v35, s0, v[140:141]
	global_store_dwordx4 v[18:19], v[26:29], off
	v_add_u32_e32 v19, 0xb0, v145
	s_waitcnt lgkmcnt(0)
	v_mul_f32_e32 v18, 0xbfb8aa3b, v20
	v_pk_mul_f32 v[10:11], v[14:15], v[10:11]
	v_pk_mul_f32 v[16:17], v[16:17], v[18:19] op_sel_hi:[1,0]
	v_pk_mul_f32 v[14:15], v[14:15], v[18:19] op_sel_hi:[1,0]
	v_pk_mul_f32 v[2:3], v[6:7], v[2:3]
	v_pk_mul_f32 v[6:7], v[6:7], v[18:19] op_sel_hi:[1,0]
	v_exp_f32_e32 v14, v14
	v_exp_f32_e32 v15, v15
	v_exp_f32_e32 v16, v16
	v_exp_f32_e32 v17, v17
	v_exp_f32_e32 v6, v6
	v_exp_f32_e32 v7, v7
	v_pk_mul_f32 v[4:5], v[8:9], v[4:5]
	v_pk_mul_f32 v[8:9], v[8:9], v[18:19] op_sel_hi:[1,0]
	v_pk_add_f32 v[16:17], v[16:17], 1.0 op_sel_hi:[1,0]
	v_exp_f32_e32 v8, v8
	v_exp_f32_e32 v9, v9
	v_pk_add_f32 v[14:15], v[14:15], 1.0 op_sel_hi:[1,0]
	v_pk_add_f32 v[6:7], v[6:7], 1.0 op_sel_hi:[1,0]
	v_rcp_f32_e32 v14, v14
	v_rcp_f32_e32 v15, v15
	v_rcp_f32_e32 v16, v16
	v_rcp_f32_e32 v17, v17
	v_rcp_f32_e32 v6, v6
	v_rcp_f32_e32 v7, v7
	v_pk_add_f32 v[8:9], v[8:9], 1.0 op_sel_hi:[1,0]
	v_mul_f32_e32 v20, v20, v20
	v_rcp_f32_e32 v8, v8
	v_rcp_f32_e32 v9, v9
	v_pk_mul_f32 v[16:17], v[20:21], v[16:17] op_sel_hi:[0,1]
	v_pk_mul_f32 v[14:15], v[20:21], v[14:15] op_sel_hi:[0,1]
	v_pk_mul_f32 v[6:7], v[20:21], v[6:7] op_sel_hi:[0,1]
	v_pk_mul_f32 v[12:13], v[12:13], v[16:17]
	v_pk_mul_f32 v[10:11], v[10:11], v[14:15]
	v_pk_mul_f32 v[2:3], v[2:3], v[6:7]
	v_cvt_pk_bf16_f32 v10, v10, v11
	v_cvt_pk_bf16_f32 v11, v12, v13
	v_pk_mul_f32 v[8:9], v[20:21], v[8:9] op_sel_hi:[0,1]
	v_cvt_pk_bf16_f32 v12, v2, v3
	v_mad_i64_i32 v[2:3], s[20:21], v19, s0, v[140:141]
	s_mov_b64 s[20:21], -1
	s_andn2_b64 vcc, exec, s[4:5]
	v_pk_mul_f32 v[4:5], v[4:5], v[8:9]
	s_nop 0
	v_cvt_pk_bf16_f32 v13, v4, v5
	global_store_dwordx4 v[2:3], v[10:13], off
	s_cbranch_vccnz .LBB0_155
	s_andn2_b64 vcc, exec, s[8:9]
	s_cbranch_vccnz .LBB0_154
	s_barrier
	s_branch .LBB0_154
